# v36 + the four GEMM K-loop heads aligned to 64 bytes (p2align 6)
# speedup vs baseline: 1.0057x; 1.0057x over previous
; template <class Epi, class Sched, bool ALIGN_EPI = false, bool SP2 = false>
; __device__ __forceinline__ void gemm_phase(PG8_LAS unsigned char* lds, const Gemm g, const Sched& S, const Epi& E) {
;     ...
;         const bool has_next = S.next(ui + 1, nxt);
;         const char* nA = has_next ? (const char*)g.A + (size_t)nxt.pm * tstep : cA; const char* nB = has_next ? (const char*)g.Bt + (size_t)nxt.pn * tstep : cB;
;         for (int t = 0; t < nt; t += 2) {
;             const bool last = (t == nt - 2);
;             const char* a1 = cA + (size_t)(t + 1) * kstep;
;             const char* a2 = last ? nA : cA + (size_t)(t + 2) * kstep; const char* b2 = last ? nB : cB + (size_t)(t + 2) * kstep;
;             const char* a3 = a2 + kstep; const char* b3 = b2 + kstep;
;             if (last && has_next) S.a_ready(nxt);
;     ...
; #pragma unroll
;         for (int a = 0; a < 2; ++a)
; #pragma unroll
;             for (int b = 0; b < 2; ++b)
; #pragma unroll
;                 for (int m = 0; m < 4; ++m)
; #pragma unroll
;                     for (int n = 0; n < 2; ++n) acc[a][b][m][n] = (f32x4){0.f, 0.f, 0.f, 0.f};
.LBB0_103:
	s_ashr_i32 s23, s22, 31
	s_lshl_b64 s[24:25], s[22:23], 20
	s_add_u32 s24, s66, s24
	s_addc_u32 s25, s67, s25
	s_and_b64 s[26:27], s[0:1], exec
	s_cselect_b32 s7, s25, s5
	s_cselect_b32 s23, s24, s4
	s_ashr_i32 s21, s20, 31
	s_lshl_b64 s[26:27], s[20:21], 20
	s_add_u32 s26, s8, s26
	s_addc_u32 s27, s9, s27
	s_and_b64 s[30:31], s[0:1], exec
	s_cselect_b32 s21, s27, s3
	s_cselect_b32 s70, s26, s2
	s_add_u32 s30, s4, 0x80080
	s_addc_u32 s31, s5, 0
	s_add_u32 s71, s2, 0x100
	v_mov_b32_e32 v0, 0
	s_addc_u32 s72, s3, 0
	s_mov_b32 s73, -2
	v_mov_b32_e32 v1, v0
	v_mov_b32_e32 v2, v0
	v_mov_b32_e32 v3, v0
	v_mov_b32_e32 v4, v0
	v_mov_b32_e32 v5, v0
	v_mov_b32_e32 v6, v0
	v_mov_b32_e32 v7, v0
	v_mov_b32_e32 v8, v0
	v_mov_b32_e32 v9, v0
	v_mov_b32_e32 v10, v0
	v_mov_b32_e32 v11, v0
	v_mov_b32_e32 v12, v0
	v_mov_b32_e32 v13, v0
	v_mov_b32_e32 v14, v0
	v_mov_b32_e32 v15, v0
	v_mov_b32_e32 v24, v0
	v_mov_b32_e32 v25, v0
	v_mov_b32_e32 v26, v0
	v_mov_b32_e32 v27, v0
	v_mov_b32_e32 v28, v0
	v_mov_b32_e32 v29, v0
	v_mov_b32_e32 v30, v0
	v_mov_b32_e32 v31, v0
	v_mov_b32_e32 v40, v0
	v_mov_b32_e32 v41, v0
	v_mov_b32_e32 v42, v0
	v_mov_b32_e32 v43, v0
	v_mov_b32_e32 v44, v0
	v_mov_b32_e32 v45, v0
	v_mov_b32_e32 v46, v0
	v_mov_b32_e32 v47, v0
	v_mov_b32_e32 v16, v0
	v_mov_b32_e32 v17, v0
	v_mov_b32_e32 v18, v0
	v_mov_b32_e32 v19, v0
	v_mov_b32_e32 v20, v0
	v_mov_b32_e32 v21, v0
	v_mov_b32_e32 v22, v0
	v_mov_b32_e32 v23, v0
	v_mov_b32_e32 v32, v0
	v_mov_b32_e32 v33, v0
	v_mov_b32_e32 v34, v0
	v_mov_b32_e32 v35, v0
	v_mov_b32_e32 v36, v0
	v_mov_b32_e32 v37, v0
	v_mov_b32_e32 v38, v0
	v_mov_b32_e32 v39, v0
	v_mov_b32_e32 v48, v0
	v_mov_b32_e32 v49, v0
	v_mov_b32_e32 v50, v0
	v_mov_b32_e32 v51, v0
	v_mov_b32_e32 v52, v0
	v_mov_b32_e32 v53, v0
	v_mov_b32_e32 v54, v0
	v_mov_b32_e32 v55, v0
	v_mov_b32_e32 v56, v0
	v_mov_b32_e32 v57, v0
	v_mov_b32_e32 v58, v0
	v_mov_b32_e32 v59, v0
	v_mov_b32_e32 v60, v0
	v_mov_b32_e32 v61, v0
	v_mov_b32_e32 v62, v0
	v_mov_b32_e32 v63, v0
	v_mov_b32_e32 v64, v0
	v_mov_b32_e32 v65, v0
	v_mov_b32_e32 v66, v0
	v_mov_b32_e32 v67, v0
	v_mov_b32_e32 v68, v0
	v_mov_b32_e32 v69, v0
	v_mov_b32_e32 v70, v0
	v_mov_b32_e32 v71, v0
	v_mov_b32_e32 v72, v0
	v_mov_b32_e32 v73, v0
	v_mov_b32_e32 v74, v0
	v_mov_b32_e32 v75, v0
	v_mov_b32_e32 v76, v0
	v_mov_b32_e32 v77, v0
	v_mov_b32_e32 v78, v0
	v_mov_b32_e32 v79, v0
	v_mov_b32_e32 v88, v0
	v_mov_b32_e32 v89, v0
	v_mov_b32_e32 v90, v0
	v_mov_b32_e32 v91, v0
	v_mov_b32_e32 v92, v0
	v_mov_b32_e32 v93, v0
	v_mov_b32_e32 v94, v0
	v_mov_b32_e32 v95, v0
	v_mov_b32_e32 v104, v0
	v_mov_b32_e32 v105, v0
	v_mov_b32_e32 v106, v0
	v_mov_b32_e32 v107, v0
	v_mov_b32_e32 v108, v0
	v_mov_b32_e32 v109, v0
	v_mov_b32_e32 v110, v0
	v_mov_b32_e32 v111, v0
	v_mov_b32_e32 v80, v0
	v_mov_b32_e32 v81, v0
	v_mov_b32_e32 v82, v0
	v_mov_b32_e32 v83, v0
	v_mov_b32_e32 v84, v0
	v_mov_b32_e32 v85, v0
	v_mov_b32_e32 v86, v0
	v_mov_b32_e32 v87, v0
	v_mov_b32_e32 v96, v0
	v_mov_b32_e32 v97, v0
	v_mov_b32_e32 v98, v0
	v_mov_b32_e32 v99, v0
	v_mov_b32_e32 v100, v0
	v_mov_b32_e32 v101, v0
	v_mov_b32_e32 v102, v0
	v_mov_b32_e32 v103, v0
	v_mov_b32_e32 v112, v0
	v_mov_b32_e32 v113, v0
	v_mov_b32_e32 v114, v0
	v_mov_b32_e32 v115, v0
	v_mov_b32_e32 v116, v0
	v_mov_b32_e32 v117, v0
	v_mov_b32_e32 v118, v0
	v_mov_b32_e32 v119, v0
	v_mov_b32_e32 v120, v0
	v_mov_b32_e32 v121, v0
	v_mov_b32_e32 v122, v0
	v_mov_b32_e32 v123, v0
	v_mov_b32_e32 v124, v0
	v_mov_b32_e32 v125, v0
	v_mov_b32_e32 v126, v0
	v_mov_b32_e32 v127, v0
	.p2align 6

; template <class Epi, class Sched, bool ALIGN_EPI = false, bool SP2 = false>
; __device__ __forceinline__ void gemm_phase(PG8_LAS unsigned char* lds, const Gemm g, const Sched& S, const Epi& E) {
;     ...
;         const bool has_next = S.next(ui + 1, nxt);
;         const char* nA = has_next ? (const char*)g.A + (size_t)nxt.pm * tstep : cA; const char* nB = has_next ? (const char*)g.Bt + (size_t)nxt.pn * tstep : cB;
;         for (int t = 0; t < nt; t += 2) {
;             const bool last = (t == nt - 2);
;             const char* a1 = cA + (size_t)(t + 1) * kstep;
;             const char* a2 = last ? nA : cA + (size_t)(t + 2) * kstep; const char* b2 = last ? nB : cB + (size_t)(t + 2) * kstep;
;             const char* a3 = a2 + kstep; const char* b3 = b2 + kstep;
;             if (last && has_next) S.a_ready(nxt);
;     ...
; #pragma unroll
;         for (int a = 0; a < 2; ++a)
; #pragma unroll
;             for (int b = 0; b < 2; ++b)
; #pragma unroll
;                 for (int m = 0; m < 4; ++m)
; #pragma unroll
;                     for (int n = 0; n < 2; ++n) acc[a][b][m][n] = (f32x4){0.f, 0.f, 0.f, 0.f};
.LBB0_526:
	s_ashr_i32 s21, s20, 31
	s_lshl_b64 s[22:23], s[20:21], 20
	s_add_u32 s22, s56, s22
	s_addc_u32 s23, s57, s23
	s_and_b64 s[24:25], s[4:5], exec
	s_cselect_b32 s21, s23, s29
	s_cselect_b32 s27, s22, s28
	s_ashr_i32 s19, s18, 31
	s_lshl_b64 s[24:25], s[18:19], 20
	s_add_u32 s24, s88, s24
	s_addc_u32 s25, s89, s25
	s_and_b64 s[30:31], s[4:5], exec
	s_cselect_b32 s19, s25, s3
	s_cselect_b32 s51, s24, s2
	s_add_u32 s28, s28, 0x80080
	s_addc_u32 s29, s29, 0
	s_add_u32 s52, s2, 0x100
	v_mov_b32_e32 v0, 0
	s_addc_u32 s53, s3, 0
	s_mov_b32 s58, -2
	s_waitcnt lgkmcnt(0)
	v_mov_b32_e32 v1, v0
	v_mov_b32_e32 v2, v0
	v_mov_b32_e32 v3, v0
	v_mov_b32_e32 v4, v0
	v_mov_b32_e32 v5, v0
	v_mov_b32_e32 v6, v0
	v_mov_b32_e32 v7, v0
	v_mov_b32_e32 v16, v0
	v_mov_b32_e32 v17, v0
	v_mov_b32_e32 v18, v0
	v_mov_b32_e32 v19, v0
	v_mov_b32_e32 v20, v0
	v_mov_b32_e32 v21, v0
	v_mov_b32_e32 v22, v0
	v_mov_b32_e32 v23, v0
	v_mov_b32_e32 v32, v0
	v_mov_b32_e32 v33, v0
	v_mov_b32_e32 v34, v0
	v_mov_b32_e32 v35, v0
	v_mov_b32_e32 v36, v0
	v_mov_b32_e32 v37, v0
	v_mov_b32_e32 v38, v0
	v_mov_b32_e32 v39, v0
	v_mov_b32_e32 v48, v0
	v_mov_b32_e32 v49, v0
	v_mov_b32_e32 v50, v0
	v_mov_b32_e32 v51, v0
	v_mov_b32_e32 v52, v0
	v_mov_b32_e32 v53, v0
	v_mov_b32_e32 v54, v0
	v_mov_b32_e32 v55, v0
	v_mov_b32_e32 v8, v0
	v_mov_b32_e32 v9, v0
	v_mov_b32_e32 v10, v0
	v_mov_b32_e32 v11, v0
	v_mov_b32_e32 v12, v0
	v_mov_b32_e32 v13, v0
	v_mov_b32_e32 v14, v0
	v_mov_b32_e32 v15, v0
	v_mov_b32_e32 v24, v0
	v_mov_b32_e32 v25, v0
	v_mov_b32_e32 v26, v0
	v_mov_b32_e32 v27, v0
	v_mov_b32_e32 v28, v0
	v_mov_b32_e32 v29, v0
	v_mov_b32_e32 v30, v0
	v_mov_b32_e32 v31, v0
	v_mov_b32_e32 v40, v0
	v_mov_b32_e32 v41, v0
	v_mov_b32_e32 v42, v0
	v_mov_b32_e32 v43, v0
	v_mov_b32_e32 v44, v0
	v_mov_b32_e32 v45, v0
	v_mov_b32_e32 v46, v0
	v_mov_b32_e32 v47, v0
	v_mov_b32_e32 v56, v0
	v_mov_b32_e32 v57, v0
	v_mov_b32_e32 v58, v0
	v_mov_b32_e32 v59, v0
	v_mov_b32_e32 v60, v0
	v_mov_b32_e32 v61, v0
	v_mov_b32_e32 v62, v0
	v_mov_b32_e32 v63, v0
	v_mov_b32_e32 v64, v0
	v_mov_b32_e32 v65, v0
	v_mov_b32_e32 v66, v0
	v_mov_b32_e32 v67, v0
	v_mov_b32_e32 v68, v0
	v_mov_b32_e32 v69, v0
	v_mov_b32_e32 v70, v0
	v_mov_b32_e32 v71, v0
	v_mov_b32_e32 v80, v0
	v_mov_b32_e32 v81, v0
	v_mov_b32_e32 v82, v0
	v_mov_b32_e32 v83, v0
	v_mov_b32_e32 v84, v0
	v_mov_b32_e32 v85, v0
	v_mov_b32_e32 v86, v0
	v_mov_b32_e32 v87, v0
	v_mov_b32_e32 v96, v0
	v_mov_b32_e32 v97, v0
	v_mov_b32_e32 v98, v0
	v_mov_b32_e32 v99, v0
	v_mov_b32_e32 v100, v0
	v_mov_b32_e32 v101, v0
	v_mov_b32_e32 v102, v0
	v_mov_b32_e32 v103, v0
	v_mov_b32_e32 v112, v0
	v_mov_b32_e32 v113, v0
	v_mov_b32_e32 v114, v0
	v_mov_b32_e32 v115, v0
	v_mov_b32_e32 v116, v0
	v_mov_b32_e32 v117, v0
	v_mov_b32_e32 v118, v0
	v_mov_b32_e32 v119, v0
	v_mov_b32_e32 v72, v0
	v_mov_b32_e32 v73, v0
	v_mov_b32_e32 v74, v0
	v_mov_b32_e32 v75, v0
	v_mov_b32_e32 v76, v0
	v_mov_b32_e32 v77, v0
	v_mov_b32_e32 v78, v0
	v_mov_b32_e32 v79, v0
	v_mov_b32_e32 v88, v0
	v_mov_b32_e32 v89, v0
	v_mov_b32_e32 v90, v0
	v_mov_b32_e32 v91, v0
	v_mov_b32_e32 v92, v0
	v_mov_b32_e32 v93, v0
	v_mov_b32_e32 v94, v0
	v_mov_b32_e32 v95, v0
	v_mov_b32_e32 v104, v0
	v_mov_b32_e32 v105, v0
	v_mov_b32_e32 v106, v0
	v_mov_b32_e32 v107, v0
	v_mov_b32_e32 v108, v0
	v_mov_b32_e32 v109, v0
	v_mov_b32_e32 v110, v0
	v_mov_b32_e32 v111, v0
	v_mov_b32_e32 v120, v0
	v_mov_b32_e32 v121, v0
	v_mov_b32_e32 v122, v0
	v_mov_b32_e32 v123, v0
	v_mov_b32_e32 v124, v0
	v_mov_b32_e32 v125, v0
	v_mov_b32_e32 v126, v0
	v_mov_b32_e32 v127, v0
	.p2align 6

; template <class Epi, class Sched, bool ALIGN_EPI = false, bool SP2 = false>
; __device__ __forceinline__ void gemm_phase(PG8_LAS unsigned char* lds, const Gemm g, const Sched& S, const Epi& E) {
;     ...
;         const bool has_next = S.next(ui + 1, nxt);
;         const char* nA = has_next ? (const char*)g.A + (size_t)nxt.pm * tstep : cA; const char* nB = has_next ? (const char*)g.Bt + (size_t)nxt.pn * tstep : cB;
;         for (int t = 0; t < nt; t += 2) {
;             const bool last = (t == nt - 2);
;             const char* a1 = cA + (size_t)(t + 1) * kstep;
;             const char* a2 = last ? nA : cA + (size_t)(t + 2) * kstep; const char* b2 = last ? nB : cB + (size_t)(t + 2) * kstep;
;             const char* a3 = a2 + kstep; const char* b3 = b2 + kstep;
;             if (last && has_next) S.a_ready(nxt);
;     ...
; #pragma unroll
;         for (int a = 0; a < 2; ++a)
; #pragma unroll
;             for (int b = 0; b < 2; ++b)
; #pragma unroll
;                 for (int m = 0; m < 4; ++m)
; #pragma unroll
;                     for (int n = 0; n < 2; ++n) acc[a][b][m][n] = (f32x4){0.f, 0.f, 0.f, 0.f};
.LBB0_628:
	s_ashr_i32 s23, s22, 31
	s_lshl_b64 s[24:25], s[22:23], 20
	s_add_u32 s24, s66, s24
	s_addc_u32 s25, s67, s25
	s_and_b64 s[26:27], s[0:1], exec
	s_cselect_b32 s23, s25, s31
	s_cselect_b32 s52, s24, s30
	s_ashr_i32 s21, s20, 31
	s_lshl_b64 s[26:27], s[20:21], 20
	s_add_u32 s26, s86, s26
	s_addc_u32 s27, s87, s27
	s_and_b64 s[34:35], s[0:1], exec
	s_cselect_b32 s21, s27, s3
	s_cselect_b32 s53, s26, s2
	s_add_u32 s30, s30, 0x80080
	s_addc_u32 s31, s31, 0
	s_add_u32 s56, s2, 0x100
	v_mov_b32_e32 v0, 0
	s_addc_u32 s57, s3, 0
	s_mov_b32 s58, -2
	v_mov_b32_e32 v1, v0
	v_mov_b32_e32 v2, v0
	v_mov_b32_e32 v3, v0
	v_mov_b32_e32 v4, v0
	v_mov_b32_e32 v5, v0
	v_mov_b32_e32 v6, v0
	v_mov_b32_e32 v7, v0
	v_mov_b32_e32 v16, v0
	v_mov_b32_e32 v17, v0
	v_mov_b32_e32 v18, v0
	v_mov_b32_e32 v19, v0
	v_mov_b32_e32 v20, v0
	v_mov_b32_e32 v21, v0
	v_mov_b32_e32 v22, v0
	v_mov_b32_e32 v23, v0
	v_mov_b32_e32 v32, v0
	v_mov_b32_e32 v33, v0
	v_mov_b32_e32 v34, v0
	v_mov_b32_e32 v35, v0
	v_mov_b32_e32 v36, v0
	v_mov_b32_e32 v37, v0
	v_mov_b32_e32 v38, v0
	v_mov_b32_e32 v39, v0
	v_mov_b32_e32 v48, v0
	v_mov_b32_e32 v49, v0
	v_mov_b32_e32 v50, v0
	v_mov_b32_e32 v51, v0
	v_mov_b32_e32 v52, v0
	v_mov_b32_e32 v53, v0
	v_mov_b32_e32 v54, v0
	v_mov_b32_e32 v55, v0
	v_mov_b32_e32 v8, v0
	v_mov_b32_e32 v9, v0
	v_mov_b32_e32 v10, v0
	v_mov_b32_e32 v11, v0
	v_mov_b32_e32 v12, v0
	v_mov_b32_e32 v13, v0
	v_mov_b32_e32 v14, v0
	v_mov_b32_e32 v15, v0
	v_mov_b32_e32 v24, v0
	v_mov_b32_e32 v25, v0
	v_mov_b32_e32 v26, v0
	v_mov_b32_e32 v27, v0
	v_mov_b32_e32 v28, v0
	v_mov_b32_e32 v29, v0
	v_mov_b32_e32 v30, v0
	v_mov_b32_e32 v31, v0
	v_mov_b32_e32 v40, v0
	v_mov_b32_e32 v41, v0
	v_mov_b32_e32 v42, v0
	v_mov_b32_e32 v43, v0
	v_mov_b32_e32 v44, v0
	v_mov_b32_e32 v45, v0
	v_mov_b32_e32 v46, v0
	v_mov_b32_e32 v47, v0
	v_mov_b32_e32 v56, v0
	v_mov_b32_e32 v57, v0
	v_mov_b32_e32 v58, v0
	v_mov_b32_e32 v59, v0
	v_mov_b32_e32 v60, v0
	v_mov_b32_e32 v61, v0
	v_mov_b32_e32 v62, v0
	v_mov_b32_e32 v63, v0
	v_mov_b32_e32 v64, v0
	v_mov_b32_e32 v65, v0
	v_mov_b32_e32 v66, v0
	v_mov_b32_e32 v67, v0
	v_mov_b32_e32 v68, v0
	v_mov_b32_e32 v69, v0
	v_mov_b32_e32 v70, v0
	v_mov_b32_e32 v71, v0
	v_mov_b32_e32 v80, v0
	v_mov_b32_e32 v81, v0
	v_mov_b32_e32 v82, v0
	v_mov_b32_e32 v83, v0
	v_mov_b32_e32 v84, v0
	v_mov_b32_e32 v85, v0
	v_mov_b32_e32 v86, v0
	v_mov_b32_e32 v87, v0
	v_mov_b32_e32 v96, v0
	v_mov_b32_e32 v97, v0
	v_mov_b32_e32 v98, v0
	v_mov_b32_e32 v99, v0
	v_mov_b32_e32 v100, v0
	v_mov_b32_e32 v101, v0
	v_mov_b32_e32 v102, v0
	v_mov_b32_e32 v103, v0
	v_mov_b32_e32 v112, v0
	v_mov_b32_e32 v113, v0
	v_mov_b32_e32 v114, v0
	v_mov_b32_e32 v115, v0
	v_mov_b32_e32 v116, v0
	v_mov_b32_e32 v117, v0
	v_mov_b32_e32 v118, v0
	v_mov_b32_e32 v119, v0
	v_mov_b32_e32 v72, v0
	v_mov_b32_e32 v73, v0
	v_mov_b32_e32 v74, v0
	v_mov_b32_e32 v75, v0
	v_mov_b32_e32 v76, v0
	v_mov_b32_e32 v77, v0
	v_mov_b32_e32 v78, v0
	v_mov_b32_e32 v79, v0
	v_mov_b32_e32 v88, v0
	v_mov_b32_e32 v89, v0
	v_mov_b32_e32 v90, v0
	v_mov_b32_e32 v91, v0
	v_mov_b32_e32 v92, v0
	v_mov_b32_e32 v93, v0
	v_mov_b32_e32 v94, v0
	v_mov_b32_e32 v95, v0
	v_mov_b32_e32 v104, v0
	v_mov_b32_e32 v105, v0
	v_mov_b32_e32 v106, v0
	v_mov_b32_e32 v107, v0
	v_mov_b32_e32 v108, v0
	v_mov_b32_e32 v109, v0
	v_mov_b32_e32 v110, v0
	v_mov_b32_e32 v111, v0
	v_mov_b32_e32 v120, v0
	v_mov_b32_e32 v121, v0
	v_mov_b32_e32 v122, v0
	v_mov_b32_e32 v123, v0
	v_mov_b32_e32 v124, v0
	v_mov_b32_e32 v125, v0
	v_mov_b32_e32 v126, v0
	v_mov_b32_e32 v127, v0
	.p2align 6

; template <class Epi, class Sched, bool ALIGN_EPI = false, bool SP2 = false>
; __device__ __forceinline__ void gemm_phase(PG8_LAS unsigned char* lds, const Gemm g, const Sched& S, const Epi& E) {
;     ...
;         const bool has_next = S.next(ui + 1, nxt);
;         const char* nA = has_next ? (const char*)g.A + (size_t)nxt.pm * tstep : cA; const char* nB = has_next ? (const char*)g.Bt + (size_t)nxt.pn * tstep : cB;
;         for (int t = 0; t < nt; t += 2) {
;             const bool last = (t == nt - 2);
;             const char* a1 = cA + (size_t)(t + 1) * kstep;
;             const char* a2 = last ? nA : cA + (size_t)(t + 2) * kstep; const char* b2 = last ? nB : cB + (size_t)(t + 2) * kstep;
;             const char* a3 = a2 + kstep; const char* b3 = b2 + kstep;
;             if (last && has_next) S.a_ready(nxt);
;     ...
; #pragma unroll
;         for (int a = 0; a < 2; ++a)
; #pragma unroll
;             for (int b = 0; b < 2; ++b)
; #pragma unroll
;                 for (int m = 0; m < 4; ++m)
; #pragma unroll
;                     for (int n = 0; n < 2; ++n) acc[a][b][m][n] = (f32x4){0.f, 0.f, 0.f, 0.f};
.LBB0_716:
	s_ashr_i32 s21, s20, 31
	s_lshl_b64 s[22:23], s[20:21], 22
	s_add_u32 s22, s54, s22
	s_addc_u32 s23, s55, s23
	s_and_b64 s[24:25], s[0:1], exec
	s_cselect_b32 s21, s23, s29
	s_cselect_b32 s46, s22, s28
	s_ashr_i32 s19, s18, 31
	s_lshl_b64 s[24:25], s[18:19], 22
	s_add_u32 s24, s84, s24
	s_addc_u32 s25, s85, s25
	s_and_b64 s[30:31], s[0:1], exec
	s_cselect_b32 s19, s25, s3
	s_cselect_b32 s47, s24, s2
	s_add_u32 s28, s28, 0x200080
	s_addc_u32 s29, s29, 0
	s_add_u32 s48, s2, 0x100
	v_mov_b32_e32 v0, 0
	s_addc_u32 s49, s3, 0
	s_mov_b32 s50, -2
	v_mov_b32_e32 v1, v0
	v_mov_b32_e32 v2, v0
	v_mov_b32_e32 v3, v0
	v_mov_b32_e32 v4, v0
	v_mov_b32_e32 v5, v0
	v_mov_b32_e32 v6, v0
	v_mov_b32_e32 v7, v0
	v_mov_b32_e32 v16, v0
	v_mov_b32_e32 v17, v0
	v_mov_b32_e32 v18, v0
	v_mov_b32_e32 v19, v0
	v_mov_b32_e32 v20, v0
	v_mov_b32_e32 v21, v0
	v_mov_b32_e32 v22, v0
	v_mov_b32_e32 v23, v0
	v_mov_b32_e32 v32, v0
	v_mov_b32_e32 v33, v0
	v_mov_b32_e32 v34, v0
	v_mov_b32_e32 v35, v0
	v_mov_b32_e32 v36, v0
	v_mov_b32_e32 v37, v0
	v_mov_b32_e32 v38, v0
	v_mov_b32_e32 v39, v0
	v_mov_b32_e32 v48, v0
	v_mov_b32_e32 v49, v0
	v_mov_b32_e32 v50, v0
	v_mov_b32_e32 v51, v0
	v_mov_b32_e32 v52, v0
	v_mov_b32_e32 v53, v0
	v_mov_b32_e32 v54, v0
	v_mov_b32_e32 v55, v0
	v_mov_b32_e32 v8, v0
	v_mov_b32_e32 v9, v0
	v_mov_b32_e32 v10, v0
	v_mov_b32_e32 v11, v0
	v_mov_b32_e32 v12, v0
	v_mov_b32_e32 v13, v0
	v_mov_b32_e32 v14, v0
	v_mov_b32_e32 v15, v0
	v_mov_b32_e32 v24, v0
	v_mov_b32_e32 v25, v0
	v_mov_b32_e32 v26, v0
	v_mov_b32_e32 v27, v0
	v_mov_b32_e32 v28, v0
	v_mov_b32_e32 v29, v0
	v_mov_b32_e32 v30, v0
	v_mov_b32_e32 v31, v0
	v_mov_b32_e32 v40, v0
	v_mov_b32_e32 v41, v0
	v_mov_b32_e32 v42, v0
	v_mov_b32_e32 v43, v0
	v_mov_b32_e32 v44, v0
	v_mov_b32_e32 v45, v0
	v_mov_b32_e32 v46, v0
	v_mov_b32_e32 v47, v0
	v_mov_b32_e32 v56, v0
	v_mov_b32_e32 v57, v0
	v_mov_b32_e32 v58, v0
	v_mov_b32_e32 v59, v0
	v_mov_b32_e32 v60, v0
	v_mov_b32_e32 v61, v0
	v_mov_b32_e32 v62, v0
	v_mov_b32_e32 v63, v0
	v_mov_b32_e32 v64, v0
	v_mov_b32_e32 v65, v0
	v_mov_b32_e32 v66, v0
	v_mov_b32_e32 v67, v0
	v_mov_b32_e32 v68, v0
	v_mov_b32_e32 v69, v0
	v_mov_b32_e32 v70, v0
	v_mov_b32_e32 v71, v0
	v_mov_b32_e32 v80, v0
	v_mov_b32_e32 v81, v0
	v_mov_b32_e32 v82, v0
	v_mov_b32_e32 v83, v0
	v_mov_b32_e32 v84, v0
	v_mov_b32_e32 v85, v0
	v_mov_b32_e32 v86, v0
	v_mov_b32_e32 v87, v0
	v_mov_b32_e32 v96, v0
	v_mov_b32_e32 v97, v0
	v_mov_b32_e32 v98, v0
	v_mov_b32_e32 v99, v0
	v_mov_b32_e32 v100, v0
	v_mov_b32_e32 v101, v0
	v_mov_b32_e32 v102, v0
	v_mov_b32_e32 v103, v0
	v_mov_b32_e32 v112, v0
	v_mov_b32_e32 v113, v0
	v_mov_b32_e32 v114, v0
	v_mov_b32_e32 v115, v0
	v_mov_b32_e32 v116, v0
	v_mov_b32_e32 v117, v0
	v_mov_b32_e32 v118, v0
	v_mov_b32_e32 v119, v0
	v_mov_b32_e32 v72, v0
	v_mov_b32_e32 v73, v0
	v_mov_b32_e32 v74, v0
	v_mov_b32_e32 v75, v0
	v_mov_b32_e32 v76, v0
	v_mov_b32_e32 v77, v0
	v_mov_b32_e32 v78, v0
	v_mov_b32_e32 v79, v0
	v_mov_b32_e32 v88, v0
	v_mov_b32_e32 v89, v0
	v_mov_b32_e32 v90, v0
	v_mov_b32_e32 v91, v0
	v_mov_b32_e32 v92, v0
	v_mov_b32_e32 v93, v0
	v_mov_b32_e32 v94, v0
	v_mov_b32_e32 v95, v0
	v_mov_b32_e32 v104, v0
	v_mov_b32_e32 v105, v0
	v_mov_b32_e32 v106, v0
	v_mov_b32_e32 v107, v0
	v_mov_b32_e32 v108, v0
	v_mov_b32_e32 v109, v0
	v_mov_b32_e32 v110, v0
	v_mov_b32_e32 v111, v0
	v_mov_b32_e32 v120, v0
	v_mov_b32_e32 v121, v0
	v_mov_b32_e32 v122, v0
	v_mov_b32_e32 v123, v0
	v_mov_b32_e32 v124, v0
	v_mov_b32_e32 v125, v0
	v_mov_b32_e32 v126, v0
	v_mov_b32_e32 v127, v0
	.p2align 6
